# MLA inner loop rewrite (deep K/V LDS prefetch, DMA interleaved into QK, PV started before softmax, row-sum in gaps) + diff-attn producer PV MFMAs overlapped with ALiBi VALU
# speedup vs baseline: 1.0052x; 1.0052x over previous
; #define ATT_FENCE() __builtin_amdgcn_sched_barrier(0)
; __device__ __forceinline__ float attn_diff_pair(ALAS unsigned char* lds, const Args& A, int q0, f32x16 (&o)[4]) {
;     ...
;             if (actp) { ldV(fa, 0, vb); ATT_FENCE(); }
;             if (act) { mmK(fb, 3); ATT_FENCE(); }
;             if (actp) {
;                 ldV(fb, 1, vb); ATT_FENCE();
;                 mmV(fa, 0); ATT_FENCE(); ldV(fa, 2, vb); ATT_FENCE();
;                 mmV(fb, 1); ATT_FENCE(); ldV(fb, 3, vb); ATT_FENCE();
;                 mmV(fa, 2); ATT_FENCE(); mmV(fb, 3); ATT_FENCE();
;             }
;             if (act) {
.LBB0_390:
	s_and_b64 vcc, exec, s[20:21]
	s_cbranch_vccz .Ldp_fused
	ds_read_b64_tr_b16 v[4:5], v2 offset:40960
	ds_read_b64_tr_b16 v[8:9], v2 offset:41472
	ds_read_b64_tr_b16 v[12:13], v2 offset:41984
	s_waitcnt lgkmcnt(6)
	ds_read_b64_tr_b16 v[176:177], v2 offset:42496
	ds_read_b64_tr_b16 v[6:7], v2 offset:45056
	ds_read_b64_tr_b16 v[10:11], v2 offset:45568
	ds_read_b64_tr_b16 v[14:15], v2 offset:46080
	ds_read_b64_tr_b16 v[178:179], v2 offset:46592
	v_mfma_f32_32x32x16_bf16 v[66:81], v[160:163], v[204:207], v[66:81]
	s_waitcnt lgkmcnt(10)
	v_mfma_f32_32x32x16_bf16 v[50:65], v[164:167], v[204:207], v[50:65]
	s_waitcnt lgkmcnt(9)
	v_mfma_f32_32x32x16_bf16 v[34:49], v[168:171], v[204:207], v[34:49]
	s_waitcnt lgkmcnt(8)
	v_mfma_f32_32x32x16_bf16 v[18:33], v[172:175], v[204:207], v[18:33]
	ds_read_b64_tr_b16 v[160:161], v2 offset:49152
	ds_read_b64_tr_b16 v[164:165], v2 offset:49664
	ds_read_b64_tr_b16 v[168:169], v2 offset:50176
	ds_read_b64_tr_b16 v[172:173], v2 offset:50688
	ds_read_b64_tr_b16 v[162:163], v2 offset:53248
	ds_read_b64_tr_b16 v[166:167], v2 offset:53760
	ds_read_b64_tr_b16 v[170:171], v2 offset:54272
	ds_read_b64_tr_b16 v[174:175], v2 offset:54784
	s_waitcnt lgkmcnt(11)
	v_mfma_f32_32x32x16_bf16 v[66:81], v[4:7], v[200:203], v[66:81]
	s_waitcnt lgkmcnt(10)
	v_mfma_f32_32x32x16_bf16 v[50:65], v[8:11], v[200:203], v[50:65]
	s_waitcnt lgkmcnt(9)
	v_mfma_f32_32x32x16_bf16 v[34:49], v[12:15], v[200:203], v[34:49]
	s_waitcnt lgkmcnt(8)
	v_mfma_f32_32x32x16_bf16 v[18:33], v[176:179], v[200:203], v[18:33]
	ds_read_b64_tr_b16 v[176:177], v2 offset:57344
	ds_read_b64_tr_b16 v[180:181], v2 offset:57856
	ds_read_b64_tr_b16 v[184:185], v2 offset:58368
	ds_read_b64_tr_b16 v[188:189], v2 offset:58880
	ds_read_b64_tr_b16 v[178:179], v2 offset:61440
	ds_read_b64_tr_b16 v[182:183], v2 offset:61952
	ds_read_b64_tr_b16 v[186:187], v2 offset:62464
	ds_read_b64_tr_b16 v[190:191], v2 offset:62976
	s_waitcnt lgkmcnt(11)
	v_mfma_f32_32x32x16_bf16 v[66:81], v[160:163], v[196:199], v[66:81]
	s_waitcnt lgkmcnt(10)
	v_mfma_f32_32x32x16_bf16 v[50:65], v[164:167], v[196:199], v[50:65]
	s_waitcnt lgkmcnt(9)
	v_mfma_f32_32x32x16_bf16 v[34:49], v[168:171], v[196:199], v[34:49]
	s_waitcnt lgkmcnt(8)
	v_mfma_f32_32x32x16_bf16 v[18:33], v[172:175], v[196:199], v[18:33]
	s_waitcnt lgkmcnt(3)
	v_mfma_f32_32x32x16_bf16 v[66:81], v[176:179], v[192:195], v[66:81]
	s_waitcnt lgkmcnt(2)
	v_mfma_f32_32x32x16_bf16 v[50:65], v[180:183], v[192:195], v[50:65]
	s_waitcnt lgkmcnt(1)
	v_mfma_f32_32x32x16_bf16 v[34:49], v[184:187], v[192:195], v[34:49]
	s_waitcnt lgkmcnt(0)
	v_mfma_f32_32x32x16_bf16 v[18:33], v[188:191], v[192:195], v[18:33]
	s_and_b64 vcc, exec, s[20:21]
	s_cbranch_vccz .LBB0_395

; #define ALAS __attribute__((address_space(3)))
; #define ATT_FENCE() __builtin_amdgcn_sched_barrier(0)
; __device__ __forceinline__ float attn_diff_pair(ALAS unsigned char* lds, const Args& A, int q0, f32x16 (&o)[4]) {
;     ...
;             if (actp) {
;                 ldV(fb, 1, vb); ATT_FENCE();
;                 mmV(fa, 0); ATT_FENCE(); ldV(fa, 2, vb); ATT_FENCE();
;                 mmV(fb, 1); ATT_FENCE(); ldV(fb, 3, vb); ATT_FENCE();
;                 mmV(fa, 2); ATT_FENCE(); mmV(fb, 3); ATT_FENCE();
;             }
;             if (act) {
;                 const ALAS float* pk = (const ALAS float*)(lds + PR_POS + (it & 1) * 256);
;                 const f32x4 pq4 = {pqs, pqs, pqs, pqs};
; #pragma unroll
;                 for (int g = 0; g < 4; ++g) {
;                     const f32x4 p0 = *(const ALAS f32x4*)(pk + 8 * g + 4 * hiq), p1 = *(const ALAS f32x4*)(pk + 32 + 8 * g + 4 * hiq);
;                     const f32x4 d0 = pq4 - p0, d1 = pq4 - p1;
; #pragma unroll
;                     for (int j = 0; j < 4; ++j) {
;                         s0[4 * g + j] = s0[4 * g + j] - __builtin_fabsf(d0[j]);
;                         s1[4 * g + j] = s1[4 * g + j] - __builtin_fabsf(d1[j]);
;                     }
;                 }
.Ldp_fused:
	v_mov_b32_e32 v254, v2
	s_lshl_b32 s20, s35, 8
	s_add_i32 s20, s20, 0
	v_lshl_add_u32 v0, v0, 2, s20
	v_add_u32_e32 v0, 0x20000, v0
	ds_read_b64_tr_b16 v[176:177], v254 offset:40960
	ds_read_b64_tr_b16 v[180:181], v254 offset:41472
	ds_read_b64_tr_b16 v[184:185], v254 offset:41984
	ds_read_b64_tr_b16 v[188:189], v254 offset:42496
	ds_read_b64_tr_b16 v[178:179], v254 offset:45056
	ds_read_b64_tr_b16 v[182:183], v254 offset:45568
	ds_read_b64_tr_b16 v[186:187], v254 offset:46080
	ds_read_b64_tr_b16 v[190:191], v254 offset:46592
	ds_read_b128 v[2:5], v0
	ds_read_b128 v[6:9], v0 offset:32
	v_mfma_f32_32x32x16_bf16 v[66:81], v[160:163], v[204:207], v[66:81]
	v_mfma_f32_32x32x16_bf16 v[50:65], v[164:167], v[204:207], v[50:65]
	v_mfma_f32_32x32x16_bf16 v[34:49], v[168:171], v[204:207], v[34:49]
	v_mfma_f32_32x32x16_bf16 v[18:33], v[172:175], v[204:207], v[18:33]
	s_waitcnt lgkmcnt(1)
	v_sub_f32_e32 v2, v16, v2
	v_sub_f32_e32 v3, v17, v3
	v_sub_f32_e32 v4, v82, v4
	v_sub_f32_e32 v5, v83, v5
	v_mfma_f32_32x32x16_bf16 v[66:81], v[176:179], v[200:203], v[66:81]
	v_sub_f32_e64 v112, v112, |v2|
	v_sub_f32_e64 v113, v113, |v3|
	v_sub_f32_e64 v114, v114, |v4|
	v_sub_f32_e64 v115, v115, |v5|
	ds_read_b128 v[2:5], v0 offset:64
	v_mfma_f32_32x32x16_bf16 v[50:65], v[180:183], v[200:203], v[50:65]
	s_waitcnt lgkmcnt(1)
	v_sub_f32_e32 v6, v84, v6
	v_sub_f32_e32 v7, v85, v7
	v_sub_f32_e32 v8, v86, v8
	v_sub_f32_e32 v9, v87, v9
	v_mfma_f32_32x32x16_bf16 v[34:49], v[184:187], v[200:203], v[34:49]
	v_sub_f32_e64 v14, v116, |v6|
	v_sub_f32_e64 v15, v117, |v7|
	v_sub_f32_e64 v10, v118, |v8|
	v_sub_f32_e64 v11, v119, |v9|
	ds_read_b128 v[116:119], v0 offset:96
	v_mfma_f32_32x32x16_bf16 v[18:33], v[188:191], v[200:203], v[18:33]
	ds_read_b64_tr_b16 v[160:161], v254 offset:49152
	ds_read_b64_tr_b16 v[164:165], v254 offset:49664
	ds_read_b64_tr_b16 v[168:169], v254 offset:50176
	ds_read_b64_tr_b16 v[172:173], v254 offset:50688
	ds_read_b64_tr_b16 v[162:163], v254 offset:53248
	ds_read_b64_tr_b16 v[166:167], v254 offset:53760
	ds_read_b64_tr_b16 v[170:171], v254 offset:54272
	ds_read_b64_tr_b16 v[174:175], v254 offset:54784
	s_waitcnt lgkmcnt(9)
	v_sub_f32_e32 v2, v88, v2
	v_sub_f32_e32 v3, v89, v3
	v_sub_f32_e32 v4, v90, v4
	v_sub_f32_e32 v5, v91, v5
	v_sub_f32_e64 v8, v120, |v2|
	v_sub_f32_e64 v9, v121, |v3|
	v_sub_f32_e64 v6, v122, |v4|
	v_sub_f32_e64 v7, v123, |v5|
	ds_read_b128 v[120:123], v0 offset:128
	s_waitcnt lgkmcnt(9)
	v_sub_f32_e32 v116, v92, v116
	v_sub_f32_e32 v117, v93, v117
	v_sub_f32_e32 v118, v94, v118
	v_sub_f32_e32 v119, v95, v119
	v_sub_f32_e64 v4, v124, |v116|
	v_sub_f32_e64 v5, v125, |v117|
	v_sub_f32_e64 v2, v126, |v118|
	v_sub_f32_e64 v3, v127, |v119|
	ds_read_b128 v[124:127], v0 offset:160
	s_waitcnt lgkmcnt(2)
	v_mfma_f32_32x32x16_bf16 v[66:81], v[160:163], v[196:199], v[66:81]
	ds_read_b64_tr_b16 v[176:177], v254 offset:57344
	ds_read_b64_tr_b16 v[180:181], v254 offset:57856
	ds_read_b64_tr_b16 v[184:185], v254 offset:58368
	ds_read_b64_tr_b16 v[188:189], v254 offset:58880
	ds_read_b64_tr_b16 v[178:179], v254 offset:61440
	ds_read_b64_tr_b16 v[182:183], v254 offset:61952
	ds_read_b64_tr_b16 v[186:187], v254 offset:62464
	ds_read_b64_tr_b16 v[190:191], v254 offset:62976
	s_waitcnt lgkmcnt(9)
	v_sub_f32_e32 v120, v16, v120
	v_sub_f32_e32 v121, v17, v121
	v_sub_f32_e32 v122, v82, v122
	v_sub_f32_e32 v123, v83, v123
	v_mfma_f32_32x32x16_bf16 v[50:65], v[164:167], v[196:199], v[50:65]
	v_sub_f32_e64 v96, v96, |v120|
	v_sub_f32_e64 v97, v97, |v121|
	v_sub_f32_e64 v98, v98, |v122|
	v_sub_f32_e64 v99, v99, |v123|
	ds_read_b128 v[116:119], v0 offset:192
	s_waitcnt lgkmcnt(9)
	v_sub_f32_e32 v124, v84, v124
	v_sub_f32_e32 v125, v85, v125
	v_sub_f32_e32 v126, v86, v126
	v_sub_f32_e32 v127, v87, v127
	v_mfma_f32_32x32x16_bf16 v[34:49], v[168:171], v[196:199], v[34:49]
	v_sub_f32_e64 v100, v100, |v124|
	v_sub_f32_e64 v101, v101, |v125|
	v_sub_f32_e64 v102, v102, |v126|
	v_sub_f32_e64 v103, v103, |v127|
	ds_read_b128 v[120:123], v0 offset:224
	v_mfma_f32_32x32x16_bf16 v[18:33], v[172:175], v[196:199], v[18:33]
	s_waitcnt lgkmcnt(2)
	v_mfma_f32_32x32x16_bf16 v[66:81], v[176:179], v[192:195], v[66:81]
	s_waitcnt lgkmcnt(1)
	v_sub_f32_e32 v116, v88, v116
	v_sub_f32_e32 v117, v89, v117
	v_sub_f32_e32 v118, v90, v118
	v_sub_f32_e32 v119, v91, v119
	v_mfma_f32_32x32x16_bf16 v[50:65], v[180:183], v[192:195], v[50:65]
	v_sub_f32_e64 v104, v104, |v116|
	v_sub_f32_e64 v105, v105, |v117|
	v_sub_f32_e64 v106, v106, |v118|
	v_sub_f32_e64 v107, v107, |v119|
	s_waitcnt lgkmcnt(0)
	v_sub_f32_e32 v120, v92, v120
	v_sub_f32_e32 v121, v93, v121
	v_sub_f32_e32 v122, v94, v122
	v_sub_f32_e32 v123, v95, v123
	v_mfma_f32_32x32x16_bf16 v[34:49], v[184:187], v[192:195], v[34:49]
	v_sub_f32_e64 v108, v108, |v120|
	v_sub_f32_e64 v109, v109, |v121|
	v_sub_f32_e64 v12, v110, |v122|
	v_sub_f32_e64 v13, v111, |v123|
	v_mfma_f32_32x32x16_bf16 v[18:33], v[188:191], v[192:195], v[18:33]
	s_or_b32 s20, s57, 63
	s_cmp_le_i32 s20, s48
	s_branch .Ldp_after_alibi

; __device__ __forceinline__ int crow(int r, int hi) { return (r & 3) + 8 * (r >> 2) + 4 * hi; }
; __device__ __forceinline__ float attn_diff_pair(ALAS unsigned char* lds, const Args& A, int q0, f32x16 (&o)[4]) {
;     ...
;                 if (64 * t + 63 > qrow0) {
; #pragma unroll
;                     for (int r = 0; r < 16; ++r) { const int kv = 64 * t + crow(r, hi); if (kv > qidx) s0[r] = -INFINITY; if (kv + 32 > qidx) s1[r] = -INFINITY; }
;                 }
.Ldp_after_alibi:
	s_cbranch_scc1 .LBB0_397
	v_or_b32_e32 v0, s57, v243
	v_or_b32_e32 v110, 32, v0
	v_cmp_le_i32_e32 vcc, v110, v231
	v_or_b32_e32 v110, 33, v0
	s_nop 0
	v_cndmask_b32_e32 v96, v249, v96, vcc
	v_cmp_lt_i32_e32 vcc, v0, v231
	s_nop 1
	v_cndmask_b32_e32 v113, v249, v113, vcc
	v_cmp_le_i32_e32 vcc, v0, v231
	s_nop 1
	v_cndmask_b32_e32 v112, v249, v112, vcc
	v_cmp_le_i32_e32 vcc, v110, v231
	v_or_b32_e32 v110, 2, v0
	s_nop 0
	v_cndmask_b32_e32 v97, v249, v97, vcc
	v_cmp_le_i32_e32 vcc, v110, v231
	v_or_b32_e32 v110, 34, v0
	s_nop 0
	v_cndmask_b32_e32 v114, v249, v114, vcc
	v_cmp_le_i32_e32 vcc, v110, v231
	v_or_b32_e32 v110, 3, v0
	s_nop 0
	v_cndmask_b32_e32 v98, v249, v98, vcc
	v_cmp_le_i32_e32 vcc, v110, v231
	v_or_b32_e32 v110, 35, v0
	s_nop 0
	v_cndmask_b32_e32 v115, v249, v115, vcc
	v_cmp_le_i32_e32 vcc, v110, v231
	v_or_b32_e32 v110, 8, v0
	s_nop 0
	v_cndmask_b32_e32 v99, v249, v99, vcc
	v_cmp_le_i32_e32 vcc, v110, v231
	v_or_b32_e32 v110, 40, v0
	s_nop 0
	v_cndmask_b32_e32 v14, v249, v14, vcc
	v_cmp_le_i32_e32 vcc, v110, v231
	v_or_b32_e32 v110, 9, v0
	s_nop 0
	v_cndmask_b32_e32 v100, v249, v100, vcc
	v_cmp_le_i32_e32 vcc, v110, v231
	v_or_b32_e32 v110, 41, v0
	s_nop 0
	v_cndmask_b32_e32 v15, v249, v15, vcc
	v_cmp_le_i32_e32 vcc, v110, v231
	v_or_b32_e32 v110, 10, v0
	s_nop 0
	v_cndmask_b32_e32 v101, v249, v101, vcc
	v_cmp_le_i32_e32 vcc, v110, v231
	v_or_b32_e32 v110, 42, v0
	s_nop 0
	v_cndmask_b32_e32 v10, v249, v10, vcc
	v_cmp_le_i32_e32 vcc, v110, v231
	v_or_b32_e32 v110, 11, v0
	s_nop 0
	v_cndmask_b32_e32 v102, v249, v102, vcc
	v_cmp_le_i32_e32 vcc, v110, v231
	v_or_b32_e32 v110, 43, v0
	s_nop 0
	v_cndmask_b32_e32 v11, v249, v11, vcc
	v_cmp_le_i32_e32 vcc, v110, v231
	v_or_b32_e32 v110, 16, v0
	s_nop 0
	v_cndmask_b32_e32 v103, v249, v103, vcc
	v_cmp_le_i32_e32 vcc, v110, v231
	v_or_b32_e32 v110, 48, v0
	s_nop 0
	v_cndmask_b32_e32 v8, v249, v8, vcc
	v_cmp_le_i32_e32 vcc, v110, v231
	v_or_b32_e32 v110, 17, v0
	s_nop 0
	v_cndmask_b32_e32 v104, v249, v104, vcc
	v_cmp_le_i32_e32 vcc, v110, v231
	v_or_b32_e32 v110, 49, v0
	s_nop 0
	v_cndmask_b32_e32 v9, v249, v9, vcc
	v_cmp_le_i32_e32 vcc, v110, v231
	v_or_b32_e32 v110, 18, v0
	s_nop 0
	v_cndmask_b32_e32 v105, v249, v105, vcc
	v_cmp_le_i32_e32 vcc, v110, v231
	v_or_b32_e32 v110, 50, v0
	s_nop 0
	v_cndmask_b32_e32 v6, v249, v6, vcc
	v_cmp_le_i32_e32 vcc, v110, v231
	v_or_b32_e32 v110, 19, v0
	s_nop 0
	v_cndmask_b32_e32 v106, v249, v106, vcc
	v_cmp_le_i32_e32 vcc, v110, v231
	v_or_b32_e32 v110, 51, v0
	s_nop 0
	v_cndmask_b32_e32 v7, v249, v7, vcc
	v_cmp_le_i32_e32 vcc, v110, v231
	v_or_b32_e32 v110, 24, v0
	s_nop 0
	v_cndmask_b32_e32 v107, v249, v107, vcc
	v_cmp_le_i32_e32 vcc, v110, v231
	v_or_b32_e32 v110, 56, v0
	s_nop 0
	v_cndmask_b32_e32 v4, v249, v4, vcc
	v_cmp_le_i32_e32 vcc, v110, v231
	v_or_b32_e32 v110, 25, v0
	s_nop 0
	v_cndmask_b32_e32 v108, v249, v108, vcc
	v_cmp_le_i32_e32 vcc, v110, v231
	v_or_b32_e32 v110, 57, v0
	s_nop 0
	v_cndmask_b32_e32 v5, v249, v5, vcc
	v_cmp_le_i32_e32 vcc, v110, v231
	v_or_b32_e32 v110, 26, v0
	s_nop 0
	v_cndmask_b32_e32 v109, v249, v109, vcc
	v_cmp_le_i32_e32 vcc, v110, v231
	v_or_b32_e32 v110, 58, v0
	s_nop 0
	v_cndmask_b32_e32 v2, v249, v2, vcc
	v_cmp_le_i32_e32 vcc, v110, v231
	v_or_b32_e32 v110, 27, v0
	v_or_b32_e32 v0, 59, v0
	v_cndmask_b32_e32 v12, v249, v12, vcc
	v_cmp_le_i32_e32 vcc, v110, v231
	s_nop 1
	v_cndmask_b32_e32 v3, v249, v3, vcc
	v_cmp_le_i32_e32 vcc, v0, v231
	s_nop 1
	v_cndmask_b32_e32 v13, v249, v13, vcc

; #define ALAS __attribute__((address_space(3)))
; #define ATT_WAITV(n) asm volatile("s_waitcnt vmcnt(" #n ")" ::: "memory")
; __device__ __forceinline__ float attn_mla_lag(ALAS unsigned char* lds, const Args& A, int q0, f32x16 (&o)[4]) {
;     ...
;     auto qk = [&](int t) {
;         const ALAS unsigned char* kbuf = lds + KOFF + (t & 1) * KBYTES;
;         const f32x16 z = {0.f, 0.f, 0.f, 0.f, 0.f, 0.f, 0.f, 0.f, 0.f, 0.f, 0.f, 0.f, 0.f, 0.f, 0.f, 0.f};
; #pragma unroll
;         for (int s = 0; s < NSTEP; ++s) {
;             const int kb = s >> 2, ch = 2 * (s & 3) + hi;
;             const ALAS unsigned char* p = kbuf + kb * 8192 + koff + ((ch ^ kx) * 16);
;             const bf16x8 k0 = *(const ALAS bf16x8*)p, k1 = *(const ALAS bf16x8*)(p + 4096);
;             s0 = __builtin_amdgcn_mfma_f32_32x32x16_bf16(k0, qr[s], s == 0 ? z : s0, 0, 0, 0);
;             s1 = __builtin_amdgcn_mfma_f32_32x32x16_bf16(k1, qr[s], s == 0 ? z : s1, 0, 0, 0);
;         }
;         asm volatile("s_nop 15\n\ts_nop 7" : "+v"(s0), "+v"(s1));
;     ...
;     auto top = [&](int t) {
;         ATT_WAITV(0);
;         __builtin_amdgcn_s_barrier();
;         asm volatile("" ::: "memory");
;         if (t + 1 < NT) issueK(t + 1);
;         if (t < NT) issueV(t);
;     };
.LBB0_1095:
	s_waitcnt vmcnt(0)
	s_barrier
	s_add_i32 s6, s8, 1
	s_bitcmp1_b32 s8, 0
	s_cselect_b32 s9, 0x6000, 0
	v_add_u32_e32 v0, s9, v218
	v_add_u32_e32 v245, v0, v219
	v_add_u32_e32 v254, v0, v220
	ds_read_b128 v[66:69], v245
	ds_read_b128 v[70:73], v245 offset:4096
	v_add_u32_e32 v233, v0, v221
	ds_read_b128 v[246:249], v254
	ds_read_b128 v[250:253], v254 offset:4096
	v_add_u32_e32 v0, v0, v222
	ds_read_b128 v[224:227], v233
	ds_read_b128 v[228:231], v233 offset:4096
	s_bitcmp1_b32 s6, 0
	s_cselect_b32 s7, 0x6000, 0
	s_add_i32 s7, s88, s7
	s_and_b32 s9, s5, 0x4000
	s_xor_b32 s10, s9, 0x4000
	v_add_u32_e32 v234, s10, v238
	s_add_i32 s9, s88, s9
	s_add_i32 s9, s9, 0xc000
	s_mov_b32 m0, s7
	s_waitcnt lgkmcnt(5)
	v_mfma_f32_32x32x16_bf16 v[82:97], v[66:69], v[98:101], 0
	s_waitcnt lgkmcnt(4)
	v_mfma_f32_32x32x16_bf16 v[66:81], v[70:73], v[98:101], 0
	s_waitcnt lgkmcnt(3)
	v_mfma_f32_32x32x16_bf16 v[82:97], v[246:249], v[102:105], v[82:97]
	s_waitcnt lgkmcnt(2)
	v_mfma_f32_32x32x16_bf16 v[66:81], v[250:253], v[102:105], v[66:81]
	ds_read_b128 v[246:249], v0
	ds_read_b128 v[250:253], v0 offset:4096
	global_load_lds_dwordx4 v[212:213], off
	s_add_i32 m0, s7, 0x2000
	v_lshl_add_u64 v[236:237], v[212:213], 0, s[68:69]
	s_waitcnt lgkmcnt(3)
	v_mfma_f32_32x32x16_bf16 v[82:97], v[224:227], v[106:109], v[82:97]
	s_waitcnt lgkmcnt(2)
	v_mfma_f32_32x32x16_bf16 v[66:81], v[228:231], v[106:109], v[66:81]
	ds_read_b128 v[224:227], v245 offset:8192
	ds_read_b128 v[228:231], v245 offset:12288
	s_waitcnt lgkmcnt(3)
	v_mfma_f32_32x32x16_bf16 v[82:97], v[246:249], v[110:113], v[82:97]
	s_waitcnt lgkmcnt(2)
	v_mfma_f32_32x32x16_bf16 v[66:81], v[250:253], v[110:113], v[66:81]
	ds_read_b128 v[246:249], v254 offset:8192
	ds_read_b128 v[250:253], v254 offset:12288
	global_load_lds_dwordx4 v[236:237], off
	s_add_i32 m0, s7, 0x4000
	s_waitcnt lgkmcnt(3)
	v_mfma_f32_32x32x16_bf16 v[82:97], v[224:227], v[114:117], v[82:97]
	s_waitcnt lgkmcnt(2)
	v_mfma_f32_32x32x16_bf16 v[66:81], v[228:231], v[114:117], v[66:81]
	ds_read_b128 v[224:227], v233 offset:8192
	ds_read_b128 v[228:231], v233 offset:12288
	s_waitcnt lgkmcnt(3)
	v_mfma_f32_32x32x16_bf16 v[82:97], v[246:249], v[118:121], v[82:97]
	s_waitcnt lgkmcnt(2)
	v_mfma_f32_32x32x16_bf16 v[66:81], v[250:253], v[118:121], v[66:81]
	ds_read_b128 v[246:249], v0 offset:8192
	ds_read_b128 v[250:253], v0 offset:12288
	global_load_lds_dwordx4 v[214:215], off
	s_mov_b32 m0, s9
	s_waitcnt lgkmcnt(3)
	v_mfma_f32_32x32x16_bf16 v[82:97], v[224:227], v[122:125], v[82:97]
	s_waitcnt lgkmcnt(2)
	v_mfma_f32_32x32x16_bf16 v[66:81], v[228:231], v[122:125], v[66:81]
	ds_read_b128 v[224:227], v245 offset:16384
	ds_read_b128 v[228:231], v245 offset:20480
	s_waitcnt lgkmcnt(3)
	v_mfma_f32_32x32x16_bf16 v[82:97], v[246:249], v[126:129], v[82:97]
	s_waitcnt lgkmcnt(2)
	v_mfma_f32_32x32x16_bf16 v[66:81], v[250:253], v[126:129], v[66:81]
	ds_read_b128 v[246:249], v254 offset:16384
	ds_read_b128 v[250:253], v254 offset:20480
	global_load_lds_dwordx4 v[216:217], off
	s_add_i32 m0, s9, 0x2000
	v_lshl_add_u64 v[236:237], v[216:217], 0, s[78:79]
	s_waitcnt lgkmcnt(3)
	v_mfma_f32_32x32x16_bf16 v[82:97], v[224:227], v[130:133], v[82:97]
	s_waitcnt lgkmcnt(2)
	v_mfma_f32_32x32x16_bf16 v[66:81], v[228:231], v[130:133], v[66:81]
	ds_read_b128 v[224:227], v233 offset:16384
	ds_read_b128 v[228:231], v233 offset:20480
	s_waitcnt lgkmcnt(3)
	v_mfma_f32_32x32x16_bf16 v[82:97], v[246:249], v[134:137], v[82:97]
	s_waitcnt lgkmcnt(2)
	v_mfma_f32_32x32x16_bf16 v[66:81], v[250:253], v[134:137], v[66:81]
	ds_read_b128 v[246:249], v0 offset:16384
	ds_read_b128 v[250:253], v0 offset:20480
	global_load_lds_dwordx4 v[236:237], off
	s_waitcnt lgkmcnt(3)
	v_mfma_f32_32x32x16_bf16 v[82:97], v[224:227], v[138:141], v[82:97]
	s_waitcnt lgkmcnt(2)
	v_mfma_f32_32x32x16_bf16 v[66:81], v[228:231], v[138:141], v[66:81]
	ds_read_b64_tr_b16 v[224:225], v234 offset:49152
	ds_read_b64_tr_b16 v[226:227], v234 offset:51200
	ds_read_b64_tr_b16 v[228:229], v234 offset:49664
	ds_read_b64_tr_b16 v[230:231], v234 offset:51712
	s_waitcnt lgkmcnt(5)
	v_mfma_f32_32x32x16_bf16 v[82:97], v[246:249], v[142:145], v[82:97]
	s_waitcnt lgkmcnt(4)
	v_mfma_f32_32x32x16_bf16 v[66:81], v[250:253], v[142:145], v[66:81]
	ds_read_b64_tr_b16 v[246:247], v234 offset:50176
	ds_read_b64_tr_b16 v[248:249], v234 offset:52224
	ds_read_b64_tr_b16 v[250:251], v234 offset:50688
	ds_read_b64_tr_b16 v[252:253], v234 offset:52736
	s_waitcnt lgkmcnt(6)
	v_mfma_f32_32x32x16_bf16 v[18:33], v[224:227], v[158:161], v[18:33]
	ds_read_b64_tr_b16 v[224:225], v234 offset:53248
	ds_read_b64_tr_b16 v[226:227], v234 offset:55296
	s_nop 1
	s_waitcnt lgkmcnt(6)
	v_mfma_f32_32x32x16_bf16 v[50:65], v[228:231], v[158:161], v[50:65]
	ds_read_b64_tr_b16 v[228:229], v234 offset:53760
	ds_read_b64_tr_b16 v[230:231], v234 offset:55808
	v_max3_f32 v0, v82, v83, v66
	v_max3_f32 v245, v84, v85, v67
	v_max3_f32 v0, v0, v68, v69
	v_max3_f32 v245, v245, v88, v89
	v_max3_f32 v0, v0, v86, v87
	v_max3_f32 v0, v0, v70, v71
	s_waitcnt lgkmcnt(6)
	v_mfma_f32_32x32x16_bf16 v[34:49], v[246:249], v[158:161], v[34:49]
	ds_read_b64_tr_b16 v[246:247], v234 offset:54272
	ds_read_b64_tr_b16 v[248:249], v234 offset:56320
	v_max3_f32 v245, v245, v72, v73
	v_max3_f32 v0, v0, v90, v91
	v_max3_f32 v245, v245, v92, v93
	v_max3_f32 v0, v0, v74, v75
	v_max3_f32 v245, v245, v76, v77
	v_max3_f32 v0, v0, v94, v95
	s_waitcnt lgkmcnt(6)
	v_mfma_f32_32x32x16_bf16 v[2:17], v[250:253], v[158:161], v[2:17]
	ds_read_b64_tr_b16 v[250:251], v234 offset:54784
	ds_read_b64_tr_b16 v[252:253], v234 offset:56832
	v_max3_f32 v245, v245, v96, v97
	v_max3_f32 v0, v0, v78, v79
	v_max3_f32 v245, v245, v80, v81
	v_max3_f32 v0, v0, v245, v245
	v_mov_b32_e32 v235, v0
	s_waitcnt lgkmcnt(6)
; __device__ __forceinline__ unsigned cvtpk(float lo, float hi) { unsigned r; asm volatile("v_cvt_pk_bf16_f32 %0, %1, %2" : "=v"(r) : "v"(lo), "v"(hi)); return r; }
; #define MLA_PVM(i) do { if ((i) & 1) { MLA_LD((i) + 1, vl0, vh0); MLA_MM(i, vl1, vh1); } else { MLA_LD((i) + 1, vl1, vh1); MLA_MM(i, vl0, vh0); } } while (0)
; #define MLA_F() __builtin_amdgcn_sched_barrier(0)
; __device__ __forceinline__ float attn_mla_lag(ALAS unsigned char* lds, const Args& A, int q0, f32x16 (&o)[4]) {
;     ...
;             MLA_PVM(3);
;             { auto rr = __builtin_amdgcn_permlane32_swap(__float_as_uint(mx), __float_as_uint(mx), false, false); mx = __builtin_fmaxf(__uint_as_float(rr[0]), __uint_as_float(rr[1])); }
;             const float mnew = __builtin_fmaxf(mrun, mx);
;             alpha = __builtin_amdgcn_exp2f((mrun - mnew) * A.c1);
;             mrun = mnew;
;             const float nm = -mrun * A.c1;
;             f32x2 acc = {0.f, 0.f};
;             MLA_F();
;             MLA_PVM(4); MLA_EXPS(0); MLA_F();
;             MLA_PVM(5); MLA_EXPS(2); MLA_F();
;             MLA_PVM(6); MLA_EXPS(4); MLA_F();
;             MLA_PVM(7); MLA_EXPS(6); MLA_F();
;             MLA_PVM(8); MLA_EXPS(8); MLA_F();
;             MLA_PVM(9); MLA_EXPS(10); MLA_F();
;             MLA_PVM(10); MLA_EXPS(12); MLA_F();
;             MLA_PVM(11); MLA_EXPS(14); MLA_F();
;             MLA_PVM(12); lrun = __builtin_fmaf(lrun, alpha, acc.x + acc.y);
;             { u32x4 w; w.x = cvtpk(s0[0], s0[1]); w.y = cvtpk(s0[2], s0[3]); w.z = cvtpk(s0[4], s0[5]); w.w = cvtpk(s0[6], s0[7]); pa[0] = __builtin_bit_cast(bf16x8, w); } MLA_F();
;             MLA_PVM(13); { u32x4 w; w.x = cvtpk(s0[8], s0[9]); w.y = cvtpk(s0[10], s0[11]); w.z = cvtpk(s0[12], s0[13]); w.w = cvtpk(s0[14], s0[15]); pa[1] = __builtin_bit_cast(bf16x8, w); } MLA_F();
;             MLA_PVM(14); { u32x4 w; w.x = cvtpk(s1[0], s1[1]); w.y = cvtpk(s1[2], s1[3]); w.z = cvtpk(s1[4], s1[5]); w.w = cvtpk(s1[6], s1[7]); pa[2] = __builtin_bit_cast(bf16x8, w); } MLA_F();
;             MLA_PVM(15); MLA_F();
;             { u32x4 w; w.x = cvtpk(s1[8], s1[9]); w.y = cvtpk(s1[10], s1[11]); w.z = cvtpk(s1[12], s1[13]); w.w = cvtpk(s1[14], s1[15]); pa[3] = __builtin_bit_cast(bf16x8, w); }
	v_mfma_f32_32x32x16_bf16 v[18:33], v[224:227], v[154:157], v[18:33]
	ds_read_b64_tr_b16 v[224:225], v234 offset:57344
	ds_read_b64_tr_b16 v[226:227], v234 offset:59392
	v_permlane32_swap_b32_e32 v0, v235
	v_max3_f32 v245, v244, v0, v235
	v_sub_f32_e32 v0, v244, v245
	v_mul_f32_e32 v0, 0x3dd53b94, v0
	v_exp_f32_e32 v0, v0
	v_mul_f32_e32 v244, 0xbdd53b94, v245
	s_waitcnt lgkmcnt(6)
	v_mfma_f32_32x32x16_bf16 v[50:65], v[228:231], v[154:157], v[50:65]
	ds_read_b64_tr_b16 v[228:229], v234 offset:57856
	ds_read_b64_tr_b16 v[230:231], v234 offset:59904
	v_fma_f32 v82, v82, s76, v244
	v_fma_f32 v83, v83, s76, v244
	v_fma_f32 v239, v66, s76, v244
	v_fma_f32 v241, v67, s76, v244
	v_exp_f32_e32 v66, v82
	v_exp_f32_e32 v67, v83
	v_exp_f32_e32 v82, v239
	v_exp_f32_e32 v83, v241
	s_waitcnt lgkmcnt(6)
	v_mfma_f32_32x32x16_bf16 v[34:49], v[246:249], v[154:157], v[34:49]
	ds_read_b64_tr_b16 v[246:247], v234 offset:58368
	ds_read_b64_tr_b16 v[248:249], v234 offset:60416
	v_fma_f32 v84, v84, s76, v244
	v_fma_f32 v85, v85, s76, v244
	v_pk_add_f32 v[236:237], v[66:67], 0 op_sel_hi:[1,0]
	v_fma_f32 v239, v68, s76, v244
	v_fma_f32 v241, v69, s76, v244
	v_pk_add_f32 v[236:237], v[82:83], v[236:237]
	v_exp_f32_e32 v68, v84
	v_exp_f32_e32 v69, v85
	v_exp_f32_e32 v84, v239
	v_exp_f32_e32 v85, v241
	s_waitcnt lgkmcnt(6)
	v_mfma_f32_32x32x16_bf16 v[2:17], v[250:253], v[154:157], v[2:17]
	ds_read_b64_tr_b16 v[250:251], v234 offset:58880
	ds_read_b64_tr_b16 v[252:253], v234 offset:60928
	v_fma_f32 v86, v86, s76, v244
	v_fma_f32 v87, v87, s76, v244
	v_pk_add_f32 v[236:237], v[68:69], v[236:237]
	v_fma_f32 v239, v70, s76, v244
	v_fma_f32 v241, v71, s76, v244
	v_pk_add_f32 v[236:237], v[84:85], v[236:237]
	v_exp_f32_e32 v70, v86
	v_exp_f32_e32 v71, v87
	v_exp_f32_e32 v86, v239
	v_exp_f32_e32 v87, v241
	s_waitcnt lgkmcnt(6)
	v_mfma_f32_32x32x16_bf16 v[18:33], v[224:227], v[150:153], v[18:33]
	ds_read_b64_tr_b16 v[224:225], v234 offset:61440
	ds_read_b64_tr_b16 v[226:227], v234 offset:63488
	v_fma_f32 v88, v88, s76, v244
	v_fma_f32 v89, v89, s76, v244
	v_pk_add_f32 v[236:237], v[70:71], v[236:237]
	v_fma_f32 v239, v72, s76, v244
	v_fma_f32 v241, v73, s76, v244
	v_pk_add_f32 v[236:237], v[86:87], v[236:237]
	v_exp_f32_e32 v72, v88
	v_exp_f32_e32 v73, v89
	v_exp_f32_e32 v88, v239
	v_exp_f32_e32 v89, v241
	s_waitcnt lgkmcnt(6)
	v_mfma_f32_32x32x16_bf16 v[50:65], v[228:231], v[150:153], v[50:65]
	ds_read_b64_tr_b16 v[228:229], v234 offset:61952
	ds_read_b64_tr_b16 v[230:231], v234 offset:64000
	v_fma_f32 v90, v90, s76, v244
	v_fma_f32 v91, v91, s76, v244
	v_pk_add_f32 v[236:237], v[72:73], v[236:237]
	v_fma_f32 v239, v74, s76, v244
	v_fma_f32 v241, v75, s76, v244
	v_pk_add_f32 v[236:237], v[88:89], v[236:237]
	v_exp_f32_e32 v74, v90
	v_exp_f32_e32 v75, v91
	v_exp_f32_e32 v90, v239
	v_exp_f32_e32 v91, v241
	s_waitcnt lgkmcnt(6)
	v_mfma_f32_32x32x16_bf16 v[34:49], v[246:249], v[150:153], v[34:49]
	ds_read_b64_tr_b16 v[246:247], v234 offset:62464
	ds_read_b64_tr_b16 v[248:249], v234 offset:64512
	v_fma_f32 v92, v92, s76, v244
	v_fma_f32 v93, v93, s76, v244
	v_pk_add_f32 v[236:237], v[74:75], v[236:237]
	v_fma_f32 v239, v76, s76, v244
	v_fma_f32 v241, v77, s76, v244
	v_pk_add_f32 v[236:237], v[90:91], v[236:237]
	v_exp_f32_e32 v76, v92
	v_exp_f32_e32 v77, v93
	v_exp_f32_e32 v92, v239
	v_exp_f32_e32 v93, v241
	s_waitcnt lgkmcnt(6)
	v_mfma_f32_32x32x16_bf16 v[2:17], v[250:253], v[150:153], v[2:17]
	ds_read_b64_tr_b16 v[250:251], v234 offset:62976
	ds_read_b64_tr_b16 v[252:253], v234 offset:65024
	v_fma_f32 v94, v94, s76, v244
	v_fma_f32 v95, v95, s76, v244
	v_pk_add_f32 v[236:237], v[76:77], v[236:237]
	v_fma_f32 v239, v78, s76, v244
	v_fma_f32 v241, v79, s76, v244
	v_pk_add_f32 v[236:237], v[92:93], v[236:237]
	v_exp_f32_e32 v78, v94
	v_exp_f32_e32 v79, v95
	v_exp_f32_e32 v94, v239
	v_exp_f32_e32 v95, v241
	s_waitcnt lgkmcnt(6)
	v_mfma_f32_32x32x16_bf16 v[18:33], v[224:227], v[146:149], v[18:33]
	v_fma_f32 v96, v96, s76, v244
	v_fma_f32 v97, v97, s76, v244
	v_pk_add_f32 v[236:237], v[78:79], v[236:237]
	v_fma_f32 v239, v80, s76, v244
	v_fma_f32 v241, v81, s76, v244
	v_pk_add_f32 v[236:237], v[94:95], v[236:237]
	v_exp_f32_e32 v80, v96
	v_exp_f32_e32 v81, v97
	v_exp_f32_e32 v96, v239
	v_exp_f32_e32 v97, v241
	s_waitcnt lgkmcnt(4)
	v_mfma_f32_32x32x16_bf16 v[50:65], v[228:231], v[146:149], v[50:65]
	v_pk_add_f32 v[236:237], v[80:81], v[236:237]
	v_cvt_pk_bf16_f32 v158, v66, v67
	v_cvt_pk_bf16_f32 v159, v68, v69
	v_pk_add_f32 v[236:237], v[96:97], v[236:237]
	v_cvt_pk_bf16_f32 v160, v70, v71
	v_cvt_pk_bf16_f32 v161, v72, v73
	s_waitcnt lgkmcnt(2)
	v_mfma_f32_32x32x16_bf16 v[34:49], v[246:249], v[146:149], v[34:49]
	v_cvt_pk_bf16_f32 v154, v74, v75
	v_cvt_pk_bf16_f32 v155, v76, v77
	v_cvt_pk_bf16_f32 v156, v78, v79
	v_cvt_pk_bf16_f32 v157, v80, v81
	v_cvt_pk_bf16_f32 v150, v82, v83
	v_cvt_pk_bf16_f32 v151, v84, v85
	v_cvt_pk_bf16_f32 v152, v86, v87
	v_cvt_pk_bf16_f32 v153, v88, v89
	s_waitcnt lgkmcnt(0)
	v_mfma_f32_32x32x16_bf16 v[2:17], v[250:253], v[146:149], v[2:17]
	v_cvt_pk_bf16_f32 v146, v90, v91
	v_cvt_pk_bf16_f32 v147, v92, v93
	v_cvt_pk_bf16_f32 v148, v94, v95
	v_cvt_pk_bf16_f32 v149, v96, v97
	v_add_f32_e32 v246, v236, v237
	s_addk_i32 s5, 0x4000
	v_lshl_add_u64 v[216:217], v[216:217], 0, s[70:71]
	v_fmac_f32_e32 v246, v243, v0
	v_lshl_add_u64 v[214:215], v[214:215], 0, s[80:81]
	v_lshl_add_u64 v[212:213], v[212:213], 0, s[70:71]
	v_cmp_neq_f32_e32 vcc, 1.0, v0
	s_cbranch_vccz .Lmla_norescale
; __device__ __forceinline__ float attn_mla_lag(ALAS unsigned char* lds, const Args& A, int q0, f32x16 (&o)[4]) {
;     ...
;         __builtin_amdgcn_sched_barrier(0);
;         if (__any(alpha != 1.0f)) {
; #pragma unroll
;             for (int db = 0; db < NDB; ++db)
; #pragma unroll
;                 for (int r = 0; r < 16; ++r) o[db][r] *= alpha;
;         }
;     }
	v_pk_mul_f32 v[32:33], v[0:1], v[32:33] op_sel_hi:[0,1]
	v_pk_mul_f32 v[30:31], v[0:1], v[30:31] op_sel_hi:[0,1]
	v_pk_mul_f32 v[28:29], v[0:1], v[28:29] op_sel_hi:[0,1]
	v_pk_mul_f32 v[26:27], v[0:1], v[26:27] op_sel_hi:[0,1]
	v_pk_mul_f32 v[24:25], v[0:1], v[24:25] op_sel_hi:[0,1]
	v_pk_mul_f32 v[22:23], v[0:1], v[22:23] op_sel_hi:[0,1]
	v_pk_mul_f32 v[20:21], v[0:1], v[20:21] op_sel_hi:[0,1]
	v_pk_mul_f32 v[18:19], v[0:1], v[18:19] op_sel_hi:[0,1]
	v_pk_mul_f32 v[64:65], v[0:1], v[64:65] op_sel_hi:[0,1]
	v_pk_mul_f32 v[62:63], v[0:1], v[62:63] op_sel_hi:[0,1]
	v_pk_mul_f32 v[60:61], v[0:1], v[60:61] op_sel_hi:[0,1]
	v_pk_mul_f32 v[58:59], v[0:1], v[58:59] op_sel_hi:[0,1]
	v_pk_mul_f32 v[56:57], v[0:1], v[56:57] op_sel_hi:[0,1]
	v_pk_mul_f32 v[54:55], v[0:1], v[54:55] op_sel_hi:[0,1]
	v_pk_mul_f32 v[52:53], v[0:1], v[52:53] op_sel_hi:[0,1]
	v_pk_mul_f32 v[50:51], v[0:1], v[50:51] op_sel_hi:[0,1]
	v_pk_mul_f32 v[48:49], v[0:1], v[48:49] op_sel_hi:[0,1]
	v_pk_mul_f32 v[46:47], v[0:1], v[46:47] op_sel_hi:[0,1]
	v_pk_mul_f32 v[44:45], v[0:1], v[44:45] op_sel_hi:[0,1]
	v_pk_mul_f32 v[42:43], v[0:1], v[42:43] op_sel_hi:[0,1]
	v_pk_mul_f32 v[40:41], v[0:1], v[40:41] op_sel_hi:[0,1]
	v_pk_mul_f32 v[38:39], v[0:1], v[38:39] op_sel_hi:[0,1]
	v_pk_mul_f32 v[36:37], v[0:1], v[36:37] op_sel_hi:[0,1]
	v_pk_mul_f32 v[34:35], v[0:1], v[34:35] op_sel_hi:[0,1]
	v_pk_mul_f32 v[16:17], v[0:1], v[16:17] op_sel_hi:[0,1]
	v_pk_mul_f32 v[14:15], v[0:1], v[14:15] op_sel_hi:[0,1]
	v_pk_mul_f32 v[12:13], v[0:1], v[12:13] op_sel_hi:[0,1]
	v_pk_mul_f32 v[10:11], v[0:1], v[10:11] op_sel_hi:[0,1]
	v_pk_mul_f32 v[8:9], v[0:1], v[8:9] op_sel_hi:[0,1]
	v_pk_mul_f32 v[6:7], v[0:1], v[6:7] op_sel_hi:[0,1]
	v_pk_mul_f32 v[4:5], v[0:1], v[4:5] op_sel_hi:[0,1]
	v_pk_mul_f32 v[2:3], v[0:1], v[2:3] op_sel_hi:[0,1]
.Lmla_norescale:
	s_cmp_eq_u32 s4, s6
	s_cbranch_scc1 .LBB0_1104
	s_mov_b32 s8, s6
	v_mov_b32_e32 v244, v245
	v_mov_b32_e32 v243, v246
	s_branch .LBB0_1095

; __device__ __forceinline__ int crow(int r, int hi) { return (r & 3) + 8 * (r >> 2) + 4 * hi; }
; __device__ __forceinline__ float attn_mla_lag(ALAS unsigned char* lds, const Args& A, int q0, f32x16 (&o)[4]) {
;     ...
;             if (64 * t + 63 > qrow0) {
; #pragma unroll
;                 for (int r = 0; r < 16; ++r) { const int kv = 64 * t + crow(r, hi); if (kv > qidx) s0[r] = -INFINITY; if (kv + 32 > qidx) s1[r] = -INFINITY; }
;             }
;     ...
;     }
; #pragma unroll 1
;     for (int t = (ta > 1 ? ta : 1); t <= NT; ++t) gen(t);
.LBB0_1104:
	v_or_b32_e32 v224, 18, v223
	v_or_b32_e32 v225, 50, v223
	v_or_b32_e32 v226, 19, v223
	v_or_b32_e32 v227, 51, v223
	v_or_b32_e32 v228, 24, v223
	v_or_b32_e32 v229, 56, v223
	v_or_b32_e32 v230, 25, v223
	v_or_b32_e32 v231, 57, v223
	v_or_b32_e32 v234, 26, v223
	v_or_b32_e32 v235, 58, v223
	v_or_b32_e32 v236, 27, v223
	v_or_b32_e32 v237, 59, v223
	v_mov_b32_e32 v239, 0xff800000
	v_mov_b32_e32 v241, 1
	v_mov_b32_e32 v244, v245
	v_mov_b32_e32 v243, v246
	s_xor_b64 s[82:83], s[84:85], -1
	s_max_i32 s66, s1, 1
	s_cmp_gt_u32 s66, s0
	s_cbranch_scc1 .LBB0_1083
